# cv31 + weight-conversion item order within w_in / w_gate_up changed to K-block-fastest (consecutive waves write adjacent 128B pieces of the same bf16 rows -> contiguous destination writes)
# speedup vs baseline: 1.0110x; 1.0110x over previous
.Lcv_d0_GU:
	s_mov_b32 s29, 0xa8
	s_mov_b32 s31, 0x5800000
	s_mov_b32 s25, 0xb000
	s_mov_b32 s32, 0x4000000
	s_movk_i32 s38, 0x1000
	s_mov_b32 s34, 0x98
	s_and_b32 s14, s13, 31
	s_lshr_b32 s35, s13, 5
	s_lshl_b32 s48, s35, 6
	s_cmp_ge_u32 s48, 0x1600
	s_cselect_b32 s49, 0x1600, 0
	s_cselect_b32 s50, 128, 0
	s_sub_u32 s48, s48, s49
	s_lshr_b32 s39, s48, 7
	s_lshl_b32 s39, s39, 8
	s_and_b32 s48, s48, 127
	s_add_u32 s39, s39, s48
	s_add_u32 s39, s39, s50
	s_branch .Lcv_d0_common
.Lcv_d0_IN:
	s_movk_i32 s29, 0x28
	s_mov_b32 s31, 0x5800000
	s_mov_b32 s25, 0xb000
	s_mov_b32 s32, 0
	s_movk_i32 s38, 0x1000
	s_mov_b32 s34, 0x88
	s_and_b32 s14, s13, 31
	s_lshr_b32 s35, s13, 5
	s_lshl_b32 s48, s35, 6
	s_cmp_lt_u32 s48, 0x400
	s_cbranch_scc0 .Lcv_d0_in1
	s_add_u32 s39, s48, 0x800
	s_branch .Lcv_d0_common
